# v30: v27 + phase-0 adaLN modulation GEMV on exact-f32 MFMA (v_mfma_f32_32x32x2_f32), all weight loads issued up front; no LDS-broadcast VALU loop
# baseline (speedup 1.0000x reference)
.LBB0_10:
	v_add_u32_e32 v0, s40, v4
	v_add_u32_e32 v22, s40, v12
	v_add_u32_e32 v19, -16, v0
	v_cmp_gt_u32_e64 s[4:5], s41, v17
	v_add_u32_e32 v24, s40, v11
	v_add_u32_e32 v18, 0x1000, v17
	v_add_u32_e32 v23, -16, v22
	v_cmp_gt_u32_e64 s[6:7], s42, v17
	v_cndmask_b32_e64 v0, v19, v0, s[4:5]
	v_add_u32_e32 v26, s40, v10
	v_cmp_lt_u32_e32 vcc, s49, v17
	v_add_u32_e32 v25, -16, v24
	v_cmp_gt_u32_e64 s[8:9], s43, v17
	v_cmp_gt_u32_e64 s[10:11], s44, v17
	v_cmp_gt_u32_e64 s[12:13], s45, v17
	v_cmp_gt_u32_e64 s[14:15], s46, v17
	v_cmp_gt_u32_e64 s[18:19], s47, v17
	v_cmp_gt_u32_e64 s[20:21], s48, v17
	v_mov_b32_e32 v17, v18
	v_cndmask_b32_e64 v19, v13, v14, s[4:5]
	v_cndmask_b32_e64 v18, v15, v16, s[4:5]
	v_lshlrev_b64 v[20:21], 12, v[0:1]
	v_cndmask_b32_e64 v0, v23, v22, s[6:7]
	v_add_u32_e32 v28, s40, v9
	v_add_u32_e32 v27, -16, v26
	v_cndmask_b32_e64 v23, v13, v14, s[6:7]
	v_cndmask_b32_e64 v22, v15, v16, s[6:7]
	v_lshl_add_u64 v[18:19], v[18:19], 0, v[20:21]
	v_lshlrev_b64 v[20:21], 12, v[0:1]
	v_cndmask_b32_e64 v0, v25, v24, s[8:9]
	v_add_u32_e32 v29, s40, v8
	v_add_u32_e32 v32, -16, v28
	v_cndmask_b32_e64 v25, v13, v14, s[8:9]
	v_cndmask_b32_e64 v24, v15, v16, s[8:9]
	v_lshl_add_u64 v[18:19], v[18:19], 0, v[2:3]
	v_lshl_add_u64 v[20:21], v[22:23], 0, v[20:21]
	v_lshlrev_b64 v[22:23], 12, v[0:1]
	v_cndmask_b32_e64 v0, v27, v26, s[10:11]
	v_add_u32_e32 v30, s40, v7
	v_add_u32_e32 v33, -16, v29
	v_cndmask_b32_e64 v27, v13, v14, s[10:11]
	v_cndmask_b32_e64 v26, v15, v16, s[10:11]
	global_load_dword v36, v[18:19], off
	v_lshl_add_u64 v[18:19], v[20:21], 0, v[2:3]
	v_lshl_add_u64 v[20:21], v[24:25], 0, v[22:23]
	v_lshlrev_b64 v[22:23], 12, v[0:1]
	v_cndmask_b32_e64 v0, v32, v28, s[12:13]
	v_add_u32_e32 v31, s40, v6
	v_add_u32_e32 v34, -16, v30
	v_cndmask_b32_e64 v25, v13, v14, s[12:13]
	v_cndmask_b32_e64 v24, v15, v16, s[12:13]
	global_load_dword v28, v[18:19], off offset:2048
	v_lshl_add_u64 v[18:19], v[20:21], 0, v[2:3]
	v_lshl_add_u64 v[20:21], v[26:27], 0, v[22:23]
	v_lshlrev_b64 v[22:23], 12, v[0:1]
	v_cndmask_b32_e64 v0, v33, v29, s[14:15]
	v_add_u32_e32 v35, -16, v31
	v_cndmask_b32_e64 v27, v13, v14, s[14:15]
	v_cndmask_b32_e64 v26, v15, v16, s[14:15]
	global_load_dword v29, v[18:19], off
	v_lshl_add_u64 v[18:19], v[20:21], 0, v[2:3]
	v_lshl_add_u64 v[20:21], v[24:25], 0, v[22:23]
	v_lshlrev_b64 v[22:23], 12, v[0:1]
	v_cndmask_b32_e64 v0, v34, v30, s[18:19]
	v_cndmask_b32_e64 v25, v13, v14, s[18:19]
	v_cndmask_b32_e64 v24, v15, v16, s[18:19]
	global_load_dword v30, v[18:19], off offset:2048
	v_lshl_add_u64 v[18:19], v[20:21], 0, v[2:3]
	v_lshl_add_u64 v[20:21], v[26:27], 0, v[22:23]
	v_lshlrev_b64 v[22:23], 12, v[0:1]
	v_cndmask_b32_e64 v0, v35, v31, s[20:21]
	v_cndmask_b32_e64 v27, v13, v14, s[20:21]
	v_cndmask_b32_e64 v26, v15, v16, s[20:21]
	global_load_dword v31, v[18:19], off
	v_lshl_add_u64 v[18:19], v[20:21], 0, v[2:3]
	v_lshl_add_u64 v[20:21], v[24:25], 0, v[22:23]
	v_lshlrev_b64 v[22:23], 12, v[0:1]
	global_load_dword v0, v[18:19], off offset:2048
	v_lshl_add_u64 v[18:19], v[20:21], 0, v[2:3]
	v_lshl_add_u64 v[20:21], v[26:27], 0, v[22:23]
	global_load_dword v22, v[18:19], off
	v_lshl_add_u64 v[18:19], v[20:21], 0, v[2:3]
	global_load_dword v18, v[18:19], off offset:2048
	s_add_i32 s40, s40, 4
	s_or_b64 s[38:39], vcc, s[38:39]
	s_waitcnt vmcnt(7)
	v_mul_f32_e32 v19, 0xbfb8aa3b, v36
	v_exp_f32_e32 v19, v19
	s_waitcnt vmcnt(6)
	v_mul_f32_e32 v20, 0xbfb8aa3b, v28
	v_exp_f32_e32 v20, v20
	v_add_f32_e32 v19, 1.0, v19
	v_div_scale_f32 v26, s[4:5], v19, v19, v36
	v_add_f32_e32 v20, 1.0, v20
	v_rcp_f32_e32 v33, v26
	v_div_scale_f32 v34, s[4:5], v20, v20, v28
	s_waitcnt vmcnt(5)
	v_mul_f32_e32 v21, 0xbfb8aa3b, v29
	v_exp_f32_e32 v21, v21
	v_rcp_f32_e32 v38, v34
	v_fma_f32 v47, -v26, v33, 1.0
	v_div_scale_f32 v27, vcc, v36, v19, v36
	s_waitcnt vmcnt(4)
	v_mul_f32_e32 v23, 0xbfb8aa3b, v30
	v_exp_f32_e32 v23, v23
	v_add_f32_e32 v21, 1.0, v21
	v_div_scale_f32 v39, s[6:7], v21, v21, v29
	v_add_f32_e32 v23, 1.0, v23
	v_rcp_f32_e32 v41, v39
	s_waitcnt vmcnt(3)
	v_mul_f32_e32 v24, 0xbfb8aa3b, v31
	v_exp_f32_e32 v24, v24
	v_div_scale_f32 v42, s[8:9], v23, v23, v30
	s_waitcnt vmcnt(2)
	v_mul_f32_e32 v25, 0xbfb8aa3b, v0
	v_exp_f32_e32 v25, v25
	v_add_f32_e32 v24, 1.0, v24
	s_waitcnt vmcnt(1)
	v_mul_f32_e32 v32, 0xbfb8aa3b, v22
	v_exp_f32_e32 v32, v32
	s_waitcnt vmcnt(0)
	v_mul_f32_e32 v37, 0xbfb8aa3b, v18
	v_exp_f32_e32 v37, v37
	v_rcp_f32_e32 v44, v42
	v_div_scale_f32 v45, s[10:11], v24, v24, v31
	v_add_f32_e32 v25, 1.0, v25
	v_rcp_f32_e32 v49, v45
	v_div_scale_f32 v50, s[12:13], v25, v25, v0
	v_add_f32_e32 v32, 1.0, v32
	v_fmac_f32_e32 v33, v47, v33
	v_fma_f32 v47, -v34, v38, 1.0
	v_rcp_f32_e32 v52, v50
	v_div_scale_f32 v53, s[14:15], v32, v32, v22
	v_add_f32_e32 v37, 1.0, v37
	v_div_scale_f32 v35, s[4:5], v28, v20, v28
	v_mul_f32_e32 v55, v27, v33
	v_fmac_f32_e32 v38, v47, v38
	v_fma_f32 v47, -v39, v41, 1.0
	v_rcp_f32_e32 v56, v53
	v_div_scale_f32 v57, s[18:19], v37, v37, v18
	v_div_scale_f32 v40, s[6:7], v29, v21, v29
	v_fma_f32 v59, -v26, v55, v27
	v_fmac_f32_e32 v41, v47, v41
	v_mul_f32_e32 v47, v35, v38
	v_fma_f32 v60, -v42, v44, 1.0
	v_rcp_f32_e32 v61, v57
	v_div_scale_f32 v43, s[8:9], v30, v23, v30
	v_fmac_f32_e32 v55, v59, v33
	v_fma_f32 v59, -v34, v47, v35
	v_mul_f32_e32 v62, v40, v41
	v_fmac_f32_e32 v44, v60, v44
	v_fma_f32 v60, -v45, v49, 1.0
	v_div_scale_f32 v46, s[10:11], v31, v24, v31
	v_fma_f32 v26, -v26, v55, v27
	v_fmac_f32_e32 v47, v59, v38
	v_fma_f32 v27, -v39, v62, v40
	v_fmac_f32_e32 v49, v60, v49
	v_mul_f32_e32 v59, v43, v44
	v_fma_f32 v60, -v50, v52, 1.0
	v_div_scale_f32 v51, s[12:13], v0, v25, v0
	v_div_fmas_f32 v26, v26, v33, v55
	v_fma_f32 v33, -v34, v47, v35
	v_fmac_f32_e32 v62, v27, v41
	v_fma_f32 v27, -v42, v59, v43
	v_fmac_f32_e32 v52, v60, v52
	v_mul_f32_e32 v34, v46, v49
	v_fma_f32 v35, -v53, v56, 1.0
	s_mov_b64 vcc, s[4:5]
	v_div_scale_f32 v54, s[14:15], v22, v32, v22
	v_div_fixup_f32 v19, v26, v19, v36
	v_div_fmas_f32 v26, v33, v38, v47
	v_fma_f32 v33, -v39, v62, v40
	v_fmac_f32_e32 v59, v27, v44
	v_fma_f32 v27, -v45, v34, v46
	v_mul_f32_e32 v36, v51, v52
	v_fmac_f32_e32 v56, v35, v56
	v_fma_f32 v35, -v57, v61, 1.0
	s_mov_b64 vcc, s[6:7]
	v_div_scale_f32 v58, s[18:19], v18, v37, v18
	v_div_fixup_f32 v20, v26, v20, v28
	v_div_fmas_f32 v26, v33, v41, v62
	v_fma_f32 v28, -v42, v59, v43
	v_fmac_f32_e32 v34, v27, v49
	v_fma_f32 v27, -v50, v36, v51
	v_mul_f32_e32 v33, v54, v56
	v_fmac_f32_e32 v61, v35, v61
	s_mov_b64 vcc, s[8:9]
	ds_write2st64_b32 v5, v19, v20 offset1:8
	v_div_fixup_f32 v19, v26, v21, v29
	v_div_fmas_f32 v20, v28, v44, v59
	v_fma_f32 v21, -v45, v34, v46
	v_fmac_f32_e32 v36, v27, v52
	v_fma_f32 v26, -v53, v33, v54
	v_mul_f32_e32 v27, v58, v61
	s_mov_b64 vcc, s[10:11]
	v_div_fixup_f32 v20, v20, v23, v30
	v_div_fmas_f32 v21, v21, v49, v34
	v_fma_f32 v23, -v50, v36, v51
	v_fmac_f32_e32 v33, v26, v56
	v_fma_f32 v26, -v57, v27, v58
	s_mov_b64 vcc, s[12:13]
	ds_write2st64_b32 v5, v19, v20 offset0:16 offset1:24
	v_div_fixup_f32 v19, v21, v24, v31
	v_div_fmas_f32 v20, v23, v52, v36
	v_fma_f32 v21, -v53, v33, v54
	v_fmac_f32_e32 v27, v26, v61
	s_mov_b64 vcc, s[14:15]
	v_div_fixup_f32 v0, v20, v25, v0
	v_div_fmas_f32 v20, v21, v56, v33
	v_fma_f32 v21, -v57, v27, v58
	s_mov_b64 vcc, s[18:19]
	ds_write2st64_b32 v5, v19, v0 offset0:32 offset1:40
	v_div_fmas_f32 v19, v21, v61, v27
	v_div_fixup_f32 v0, v20, v32, v22
	v_div_fixup_f32 v18, v19, v37, v18
	ds_write2st64_b32 v5, v0, v18 offset0:48 offset1:56
	v_add_u32_e32 v5, 0x4000, v5
	s_andn2_b64 exec, exec, s[38:39]
	s_cbranch_execnz .LBB0_10
	s_or_b64 exec, exec, s[38:39]
	s_mul_hi_i32 s4, s2, 0x2aaaaaab
	s_lshr_b32 s5, s4, 31
	s_ashr_i32 s4, s4, 4
	s_add_i32 s10, s4, s5
	s_mul_i32 s4, s10, 0x60
	s_sub_i32 s4, s2, s4
	s_lshl_b32 s4, s4, 6
	s_lshl_b32 s13, s3, 7
	s_mul_i32 s7, s10, 0x1800000
	s_ashr_i32 s5, s4, 31
	s_or_b32 s11, s13, 0x70
	s_mul_i32 s8, s3, 0x300000
	s_mul_hi_i32 s6, s10, 0x1800000
	s_mul_hi_u32 s9, s13, 0x6000
	s_add_u32 s8, s7, s8
	s_addc_u32 s9, s6, s9
	s_lshl_b64 s[6:7], s[4:5], 2
	s_add_u32 s5, s8, s6
	s_addc_u32 s9, s9, s7
	v_and_b32_e32 v49, 63, v48
	s_add_u32 s8, s28, s5
	v_lshlrev_b32_e32 v50, 2, v49
	v_mov_b32_e32 v51, 0
	s_addc_u32 s9, s29, s9
	v_lshl_add_u64 v[52:53], s[8:9], 0, v[50:51]
	s_lshl_b32 s8, s3, 9
	s_add_i32 s8, s8, 0
	s_movk_i32 s12, 0x6000
	s_add_i32 s5, s13, -16
	s_add_i32 s13, s8, 0x10000
	s_mov_b32 s14, 0xc000
	s_mov_b32 s15, 0x12000
	s_mov_b32 s18, 0x18000
	s_mov_b32 s19, 0x1e000
	s_mov_b32 s20, 0x24000
	s_mov_b32 s21, 0x2a000
	s_mov_b32 s28, 0x30000
	s_mov_b32 s29, 0x36000
	s_mov_b32 s38, 0x3c000
	s_mov_b32 s39, 0x42000
	s_mov_b32 s40, 0x48000
	s_mov_b32 s41, 0x4e000
	s_mov_b32 s42, 0x54000
	s_mov_b32 s43, 0x5a000
	s_mov_b64 s[8:9], 0x60000
	v_mov_b32_e32 v54, v51
	v_mov_b32_e32 v55, v51
	v_mov_b32_e32 v56, v51
	v_mov_b32_e32 v57, v51
	v_mov_b32_e32 v58, v51
	v_mov_b32_e32 v59, v51
	v_mov_b32_e32 v60, v51
	v_mov_b32_e32 v61, v51
	v_mov_b32_e32 v62, v51
	v_mov_b32_e32 v63, v51
	v_mov_b32_e32 v64, v51
	v_mov_b32_e32 v65, v51
	v_mov_b32_e32 v66, v51
	v_mov_b32_e32 v67, v51
	v_mov_b32_e32 v68, v51
	v_mov_b32_e32 v69, v51
	v_mov_b32_e32 v70, v51
	v_mov_b32_e32 v71, v51
	v_mov_b32_e32 v72, v51
	v_mov_b32_e32 v73, v51
	v_mov_b32_e32 v74, v51
	v_mov_b32_e32 v75, v51
	v_mov_b32_e32 v76, v51
	v_mov_b32_e32 v77, v51
	s_waitcnt lgkmcnt(0)
	s_barrier
	v_and_b32_e32 v250, 31, v49
	v_lshrrev_b32_e32 v251, 5, v49
	s_lshl_b32 s44, s3, 9
	v_lshlrev_b32_e32 v248, 12, v250
	v_lshl_add_u32 v248, v251, 4, v248
	v_add_u32_e32 v248, s44, v248
	s_mul_i32 s45, s3, 0x1800
	s_add_i32 s45, s45, 0x18000
	v_lshlrev_b32_e32 v249, 3, v250
	v_lshl_add_u32 v249, v251, 10, v249
	v_add_u32_e32 v249, s45, v249
	v_lshlrev_b32_e32 v246, 3, v250
	v_sub_u32_e32 v246, v246, v50
	v_mul_u32_u24_e32 v251, 0x18000, v251
	v_add_u32_e32 v246, v246, v251
	v_mov_b32_e32 v247, 0
	s_mov_b32 s100, 0x6000
	s_mov_b32 s101, 0
	s_mov_b32 s44, 0x1e000
	s_mov_b32 s45, 0
	v_lshl_add_u64 v[244:245], v[52:53], 0, v[246:247]
	global_load_dwordx2 v[100:101], v[244:245], off
	v_lshl_add_u64 v[244:245], v[244:245], 0, s[100:101]
	global_load_dwordx2 v[102:103], v[244:245], off
	v_lshl_add_u64 v[244:245], v[244:245], 0, s[100:101]
	global_load_dwordx2 v[104:105], v[244:245], off
	v_lshl_add_u64 v[244:245], v[244:245], 0, s[100:101]
	global_load_dwordx2 v[106:107], v[244:245], off
	v_lshl_add_u64 v[244:245], v[244:245], 0, s[44:45]
	ds_read_b128 v[0:3], v248 offset:0
	global_load_dwordx2 v[108:109], v[244:245], off
	v_lshl_add_u64 v[244:245], v[244:245], 0, s[100:101]
	global_load_dwordx2 v[110:111], v[244:245], off
	v_lshl_add_u64 v[244:245], v[244:245], 0, s[100:101]
	global_load_dwordx2 v[112:113], v[244:245], off
	v_lshl_add_u64 v[244:245], v[244:245], 0, s[100:101]
	global_load_dwordx2 v[114:115], v[244:245], off
	v_lshl_add_u64 v[244:245], v[244:245], 0, s[44:45]
	ds_read_b128 v[4:7], v248 offset:32
	global_load_dwordx2 v[116:117], v[244:245], off
	v_lshl_add_u64 v[244:245], v[244:245], 0, s[100:101]
	global_load_dwordx2 v[118:119], v[244:245], off
	v_lshl_add_u64 v[244:245], v[244:245], 0, s[100:101]
	global_load_dwordx2 v[120:121], v[244:245], off
	v_lshl_add_u64 v[244:245], v[244:245], 0, s[100:101]
	global_load_dwordx2 v[122:123], v[244:245], off
	v_lshl_add_u64 v[244:245], v[244:245], 0, s[44:45]
	ds_read_b128 v[8:11], v248 offset:64
	global_load_dwordx2 v[124:125], v[244:245], off
	v_lshl_add_u64 v[244:245], v[244:245], 0, s[100:101]
	global_load_dwordx2 v[126:127], v[244:245], off
	v_lshl_add_u64 v[244:245], v[244:245], 0, s[100:101]
	global_load_dwordx2 v[128:129], v[244:245], off
	v_lshl_add_u64 v[244:245], v[244:245], 0, s[100:101]
	global_load_dwordx2 v[130:131], v[244:245], off
	v_lshl_add_u64 v[244:245], v[244:245], 0, s[44:45]
	ds_read_b128 v[12:15], v248 offset:96
	global_load_dwordx2 v[132:133], v[244:245], off
	v_lshl_add_u64 v[244:245], v[244:245], 0, s[100:101]
	global_load_dwordx2 v[134:135], v[244:245], off
	v_lshl_add_u64 v[244:245], v[244:245], 0, s[100:101]
	global_load_dwordx2 v[136:137], v[244:245], off
	v_lshl_add_u64 v[244:245], v[244:245], 0, s[100:101]
	global_load_dwordx2 v[138:139], v[244:245], off
	v_lshl_add_u64 v[244:245], v[244:245], 0, s[44:45]
	ds_read_b128 v[16:19], v248 offset:128
	global_load_dwordx2 v[140:141], v[244:245], off
	v_lshl_add_u64 v[244:245], v[244:245], 0, s[100:101]
	global_load_dwordx2 v[142:143], v[244:245], off
	v_lshl_add_u64 v[244:245], v[244:245], 0, s[100:101]
	global_load_dwordx2 v[144:145], v[244:245], off
	v_lshl_add_u64 v[244:245], v[244:245], 0, s[100:101]
	global_load_dwordx2 v[146:147], v[244:245], off
	v_lshl_add_u64 v[244:245], v[244:245], 0, s[44:45]
	ds_read_b128 v[20:23], v248 offset:160
	global_load_dwordx2 v[148:149], v[244:245], off
	v_lshl_add_u64 v[244:245], v[244:245], 0, s[100:101]
	global_load_dwordx2 v[150:151], v[244:245], off
	v_lshl_add_u64 v[244:245], v[244:245], 0, s[100:101]
	global_load_dwordx2 v[152:153], v[244:245], off
	v_lshl_add_u64 v[244:245], v[244:245], 0, s[100:101]
	global_load_dwordx2 v[154:155], v[244:245], off
	v_lshl_add_u64 v[244:245], v[244:245], 0, s[44:45]
	ds_read_b128 v[24:27], v248 offset:192
	global_load_dwordx2 v[156:157], v[244:245], off
	v_lshl_add_u64 v[244:245], v[244:245], 0, s[100:101]
	global_load_dwordx2 v[158:159], v[244:245], off
	v_lshl_add_u64 v[244:245], v[244:245], 0, s[100:101]
	global_load_dwordx2 v[160:161], v[244:245], off
	v_lshl_add_u64 v[244:245], v[244:245], 0, s[100:101]
	global_load_dwordx2 v[162:163], v[244:245], off
	v_lshl_add_u64 v[244:245], v[244:245], 0, s[44:45]
	ds_read_b128 v[28:31], v248 offset:224
	global_load_dwordx2 v[164:165], v[244:245], off
	v_lshl_add_u64 v[244:245], v[244:245], 0, s[100:101]
	global_load_dwordx2 v[166:167], v[244:245], off
	v_lshl_add_u64 v[244:245], v[244:245], 0, s[100:101]
	global_load_dwordx2 v[168:169], v[244:245], off
	v_lshl_add_u64 v[244:245], v[244:245], 0, s[100:101]
	global_load_dwordx2 v[170:171], v[244:245], off
	v_lshl_add_u64 v[244:245], v[244:245], 0, s[44:45]
	ds_read_b128 v[32:35], v248 offset:256
	global_load_dwordx2 v[172:173], v[244:245], off
	v_lshl_add_u64 v[244:245], v[244:245], 0, s[100:101]
	global_load_dwordx2 v[174:175], v[244:245], off
	v_lshl_add_u64 v[244:245], v[244:245], 0, s[100:101]
	global_load_dwordx2 v[176:177], v[244:245], off
	v_lshl_add_u64 v[244:245], v[244:245], 0, s[100:101]
	global_load_dwordx2 v[178:179], v[244:245], off
	v_lshl_add_u64 v[244:245], v[244:245], 0, s[44:45]
	ds_read_b128 v[36:39], v248 offset:288
	global_load_dwordx2 v[180:181], v[244:245], off
	v_lshl_add_u64 v[244:245], v[244:245], 0, s[100:101]
	global_load_dwordx2 v[182:183], v[244:245], off
	v_lshl_add_u64 v[244:245], v[244:245], 0, s[100:101]
	global_load_dwordx2 v[184:185], v[244:245], off
	v_lshl_add_u64 v[244:245], v[244:245], 0, s[100:101]
	global_load_dwordx2 v[186:187], v[244:245], off
	v_lshl_add_u64 v[244:245], v[244:245], 0, s[44:45]
	ds_read_b128 v[40:43], v248 offset:320
	global_load_dwordx2 v[188:189], v[244:245], off
	v_lshl_add_u64 v[244:245], v[244:245], 0, s[100:101]
	global_load_dwordx2 v[190:191], v[244:245], off
	v_lshl_add_u64 v[244:245], v[244:245], 0, s[100:101]
	global_load_dwordx2 v[192:193], v[244:245], off
	v_lshl_add_u64 v[244:245], v[244:245], 0, s[100:101]
	global_load_dwordx2 v[194:195], v[244:245], off
	v_lshl_add_u64 v[244:245], v[244:245], 0, s[44:45]
	ds_read_b128 v[44:47], v248 offset:352
	global_load_dwordx2 v[196:197], v[244:245], off
	v_lshl_add_u64 v[244:245], v[244:245], 0, s[100:101]
	global_load_dwordx2 v[198:199], v[244:245], off
	v_lshl_add_u64 v[244:245], v[244:245], 0, s[100:101]
	global_load_dwordx2 v[200:201], v[244:245], off
	v_lshl_add_u64 v[244:245], v[244:245], 0, s[100:101]
	global_load_dwordx2 v[202:203], v[244:245], off
	v_lshl_add_u64 v[244:245], v[244:245], 0, s[44:45]
	ds_read_b128 v[54:57], v248 offset:384
	global_load_dwordx2 v[204:205], v[244:245], off
	v_lshl_add_u64 v[244:245], v[244:245], 0, s[100:101]
	global_load_dwordx2 v[206:207], v[244:245], off
	v_lshl_add_u64 v[244:245], v[244:245], 0, s[100:101]
	global_load_dwordx2 v[208:209], v[244:245], off
	v_lshl_add_u64 v[244:245], v[244:245], 0, s[100:101]
	global_load_dwordx2 v[210:211], v[244:245], off
	v_lshl_add_u64 v[244:245], v[244:245], 0, s[44:45]
	ds_read_b128 v[58:61], v248 offset:416
	global_load_dwordx2 v[212:213], v[244:245], off
	v_lshl_add_u64 v[244:245], v[244:245], 0, s[100:101]
	global_load_dwordx2 v[214:215], v[244:245], off
	v_lshl_add_u64 v[244:245], v[244:245], 0, s[100:101]
	global_load_dwordx2 v[216:217], v[244:245], off
	v_lshl_add_u64 v[244:245], v[244:245], 0, s[100:101]
	global_load_dwordx2 v[218:219], v[244:245], off
	v_lshl_add_u64 v[244:245], v[244:245], 0, s[44:45]
	ds_read_b128 v[62:65], v248 offset:448
	global_load_dwordx2 v[220:221], v[244:245], off
	v_lshl_add_u64 v[244:245], v[244:245], 0, s[100:101]
	global_load_dwordx2 v[222:223], v[244:245], off
	v_lshl_add_u64 v[244:245], v[244:245], 0, s[100:101]
	global_load_dwordx2 v[224:225], v[244:245], off
	v_lshl_add_u64 v[244:245], v[244:245], 0, s[100:101]
	global_load_dwordx2 v[226:227], v[244:245], off
	ds_read_b128 v[66:69], v248 offset:480
	s_waitcnt lgkmcnt(0)
	s_waitcnt vmcnt(60)
	v_mfma_f32_32x32x2_f32 v[228:243], v0, v100, 0
	v_mfma_f32_32x32x2_f32 v[70:85], v0, v101, 0
	v_mfma_f32_32x32x2_f32 v[228:243], v1, v102, v[228:243]
	v_mfma_f32_32x32x2_f32 v[70:85], v1, v103, v[70:85]
	v_mfma_f32_32x32x2_f32 v[228:243], v2, v104, v[228:243]
	v_mfma_f32_32x32x2_f32 v[70:85], v2, v105, v[70:85]
	v_mfma_f32_32x32x2_f32 v[228:243], v3, v106, v[228:243]
	v_mfma_f32_32x32x2_f32 v[70:85], v3, v107, v[70:85]
	s_waitcnt vmcnt(56)
	v_mfma_f32_32x32x2_f32 v[228:243], v4, v108, v[228:243]
	v_mfma_f32_32x32x2_f32 v[70:85], v4, v109, v[70:85]
	v_mfma_f32_32x32x2_f32 v[228:243], v5, v110, v[228:243]
	v_mfma_f32_32x32x2_f32 v[70:85], v5, v111, v[70:85]
	v_mfma_f32_32x32x2_f32 v[228:243], v6, v112, v[228:243]
	v_mfma_f32_32x32x2_f32 v[70:85], v6, v113, v[70:85]
	v_mfma_f32_32x32x2_f32 v[228:243], v7, v114, v[228:243]
	v_mfma_f32_32x32x2_f32 v[70:85], v7, v115, v[70:85]
	s_waitcnt vmcnt(52)
	v_mfma_f32_32x32x2_f32 v[228:243], v8, v116, v[228:243]
	v_mfma_f32_32x32x2_f32 v[70:85], v8, v117, v[70:85]
	v_mfma_f32_32x32x2_f32 v[228:243], v9, v118, v[228:243]
	v_mfma_f32_32x32x2_f32 v[70:85], v9, v119, v[70:85]
	v_mfma_f32_32x32x2_f32 v[228:243], v10, v120, v[228:243]
	v_mfma_f32_32x32x2_f32 v[70:85], v10, v121, v[70:85]
	v_mfma_f32_32x32x2_f32 v[228:243], v11, v122, v[228:243]
	v_mfma_f32_32x32x2_f32 v[70:85], v11, v123, v[70:85]
	s_waitcnt vmcnt(48)
	v_mfma_f32_32x32x2_f32 v[228:243], v12, v124, v[228:243]
	v_mfma_f32_32x32x2_f32 v[70:85], v12, v125, v[70:85]
	v_mfma_f32_32x32x2_f32 v[228:243], v13, v126, v[228:243]
	v_mfma_f32_32x32x2_f32 v[70:85], v13, v127, v[70:85]
	v_mfma_f32_32x32x2_f32 v[228:243], v14, v128, v[228:243]
	v_mfma_f32_32x32x2_f32 v[70:85], v14, v129, v[70:85]
	v_mfma_f32_32x32x2_f32 v[228:243], v15, v130, v[228:243]
	v_mfma_f32_32x32x2_f32 v[70:85], v15, v131, v[70:85]
	s_waitcnt vmcnt(44)
	v_mfma_f32_32x32x2_f32 v[228:243], v16, v132, v[228:243]
	v_mfma_f32_32x32x2_f32 v[70:85], v16, v133, v[70:85]
	v_mfma_f32_32x32x2_f32 v[228:243], v17, v134, v[228:243]
	v_mfma_f32_32x32x2_f32 v[70:85], v17, v135, v[70:85]
	v_mfma_f32_32x32x2_f32 v[228:243], v18, v136, v[228:243]
	v_mfma_f32_32x32x2_f32 v[70:85], v18, v137, v[70:85]
	v_mfma_f32_32x32x2_f32 v[228:243], v19, v138, v[228:243]
	v_mfma_f32_32x32x2_f32 v[70:85], v19, v139, v[70:85]
	s_waitcnt vmcnt(40)
	v_mfma_f32_32x32x2_f32 v[228:243], v20, v140, v[228:243]
	v_mfma_f32_32x32x2_f32 v[70:85], v20, v141, v[70:85]
	v_mfma_f32_32x32x2_f32 v[228:243], v21, v142, v[228:243]
	v_mfma_f32_32x32x2_f32 v[70:85], v21, v143, v[70:85]
	v_mfma_f32_32x32x2_f32 v[228:243], v22, v144, v[228:243]
	v_mfma_f32_32x32x2_f32 v[70:85], v22, v145, v[70:85]
	v_mfma_f32_32x32x2_f32 v[228:243], v23, v146, v[228:243]
	v_mfma_f32_32x32x2_f32 v[70:85], v23, v147, v[70:85]
	s_waitcnt vmcnt(36)
	v_mfma_f32_32x32x2_f32 v[228:243], v24, v148, v[228:243]
	v_mfma_f32_32x32x2_f32 v[70:85], v24, v149, v[70:85]
	v_mfma_f32_32x32x2_f32 v[228:243], v25, v150, v[228:243]
	v_mfma_f32_32x32x2_f32 v[70:85], v25, v151, v[70:85]
	v_mfma_f32_32x32x2_f32 v[228:243], v26, v152, v[228:243]
	v_mfma_f32_32x32x2_f32 v[70:85], v26, v153, v[70:85]
	v_mfma_f32_32x32x2_f32 v[228:243], v27, v154, v[228:243]
	v_mfma_f32_32x32x2_f32 v[70:85], v27, v155, v[70:85]
	s_waitcnt vmcnt(32)
	v_mfma_f32_32x32x2_f32 v[228:243], v28, v156, v[228:243]
	v_mfma_f32_32x32x2_f32 v[70:85], v28, v157, v[70:85]
	v_mfma_f32_32x32x2_f32 v[228:243], v29, v158, v[228:243]
	v_mfma_f32_32x32x2_f32 v[70:85], v29, v159, v[70:85]
	v_mfma_f32_32x32x2_f32 v[228:243], v30, v160, v[228:243]
	v_mfma_f32_32x32x2_f32 v[70:85], v30, v161, v[70:85]
	v_mfma_f32_32x32x2_f32 v[228:243], v31, v162, v[228:243]
	v_mfma_f32_32x32x2_f32 v[70:85], v31, v163, v[70:85]
	s_waitcnt vmcnt(28)
	v_mfma_f32_32x32x2_f32 v[228:243], v32, v164, v[228:243]
	v_mfma_f32_32x32x2_f32 v[70:85], v32, v165, v[70:85]
	v_mfma_f32_32x32x2_f32 v[228:243], v33, v166, v[228:243]
	v_mfma_f32_32x32x2_f32 v[70:85], v33, v167, v[70:85]
	v_mfma_f32_32x32x2_f32 v[228:243], v34, v168, v[228:243]
	v_mfma_f32_32x32x2_f32 v[70:85], v34, v169, v[70:85]
	v_mfma_f32_32x32x2_f32 v[228:243], v35, v170, v[228:243]
	v_mfma_f32_32x32x2_f32 v[70:85], v35, v171, v[70:85]
	s_waitcnt vmcnt(24)
	v_mfma_f32_32x32x2_f32 v[228:243], v36, v172, v[228:243]
	v_mfma_f32_32x32x2_f32 v[70:85], v36, v173, v[70:85]
	v_mfma_f32_32x32x2_f32 v[228:243], v37, v174, v[228:243]
	v_mfma_f32_32x32x2_f32 v[70:85], v37, v175, v[70:85]
	v_mfma_f32_32x32x2_f32 v[228:243], v38, v176, v[228:243]
	v_mfma_f32_32x32x2_f32 v[70:85], v38, v177, v[70:85]
	v_mfma_f32_32x32x2_f32 v[228:243], v39, v178, v[228:243]
	v_mfma_f32_32x32x2_f32 v[70:85], v39, v179, v[70:85]
	s_waitcnt vmcnt(20)
	v_mfma_f32_32x32x2_f32 v[228:243], v40, v180, v[228:243]
	v_mfma_f32_32x32x2_f32 v[70:85], v40, v181, v[70:85]
	v_mfma_f32_32x32x2_f32 v[228:243], v41, v182, v[228:243]
	v_mfma_f32_32x32x2_f32 v[70:85], v41, v183, v[70:85]
	v_mfma_f32_32x32x2_f32 v[228:243], v42, v184, v[228:243]
	v_mfma_f32_32x32x2_f32 v[70:85], v42, v185, v[70:85]
	v_mfma_f32_32x32x2_f32 v[228:243], v43, v186, v[228:243]
	v_mfma_f32_32x32x2_f32 v[70:85], v43, v187, v[70:85]
	s_waitcnt vmcnt(16)
	v_mfma_f32_32x32x2_f32 v[228:243], v44, v188, v[228:243]
	v_mfma_f32_32x32x2_f32 v[70:85], v44, v189, v[70:85]
	v_mfma_f32_32x32x2_f32 v[228:243], v45, v190, v[228:243]
	v_mfma_f32_32x32x2_f32 v[70:85], v45, v191, v[70:85]
	v_mfma_f32_32x32x2_f32 v[228:243], v46, v192, v[228:243]
	v_mfma_f32_32x32x2_f32 v[70:85], v46, v193, v[70:85]
	v_mfma_f32_32x32x2_f32 v[228:243], v47, v194, v[228:243]
	v_mfma_f32_32x32x2_f32 v[70:85], v47, v195, v[70:85]
	s_waitcnt vmcnt(12)
	v_mfma_f32_32x32x2_f32 v[228:243], v54, v196, v[228:243]
	v_mfma_f32_32x32x2_f32 v[70:85], v54, v197, v[70:85]
	v_mfma_f32_32x32x2_f32 v[228:243], v55, v198, v[228:243]
	v_mfma_f32_32x32x2_f32 v[70:85], v55, v199, v[70:85]
	v_mfma_f32_32x32x2_f32 v[228:243], v56, v200, v[228:243]
	v_mfma_f32_32x32x2_f32 v[70:85], v56, v201, v[70:85]
	v_mfma_f32_32x32x2_f32 v[228:243], v57, v202, v[228:243]
	v_mfma_f32_32x32x2_f32 v[70:85], v57, v203, v[70:85]
	s_waitcnt vmcnt(8)
	v_mfma_f32_32x32x2_f32 v[228:243], v58, v204, v[228:243]
	v_mfma_f32_32x32x2_f32 v[70:85], v58, v205, v[70:85]
	v_mfma_f32_32x32x2_f32 v[228:243], v59, v206, v[228:243]
	v_mfma_f32_32x32x2_f32 v[70:85], v59, v207, v[70:85]
	v_mfma_f32_32x32x2_f32 v[228:243], v60, v208, v[228:243]
	v_mfma_f32_32x32x2_f32 v[70:85], v60, v209, v[70:85]
	v_mfma_f32_32x32x2_f32 v[228:243], v61, v210, v[228:243]
	v_mfma_f32_32x32x2_f32 v[70:85], v61, v211, v[70:85]
	s_waitcnt vmcnt(4)
	v_mfma_f32_32x32x2_f32 v[228:243], v62, v212, v[228:243]
	v_mfma_f32_32x32x2_f32 v[70:85], v62, v213, v[70:85]
	v_mfma_f32_32x32x2_f32 v[228:243], v63, v214, v[228:243]
	v_mfma_f32_32x32x2_f32 v[70:85], v63, v215, v[70:85]
	v_mfma_f32_32x32x2_f32 v[228:243], v64, v216, v[228:243]
	v_mfma_f32_32x32x2_f32 v[70:85], v64, v217, v[70:85]
	v_mfma_f32_32x32x2_f32 v[228:243], v65, v218, v[228:243]
	v_mfma_f32_32x32x2_f32 v[70:85], v65, v219, v[70:85]
	s_waitcnt vmcnt(0)
	v_mfma_f32_32x32x2_f32 v[228:243], v66, v220, v[228:243]
	v_mfma_f32_32x32x2_f32 v[70:85], v66, v221, v[70:85]
	v_mfma_f32_32x32x2_f32 v[228:243], v67, v222, v[228:243]
	v_mfma_f32_32x32x2_f32 v[70:85], v67, v223, v[70:85]
	v_mfma_f32_32x32x2_f32 v[228:243], v68, v224, v[228:243]
	v_mfma_f32_32x32x2_f32 v[70:85], v68, v225, v[70:85]
	v_mfma_f32_32x32x2_f32 v[228:243], v69, v226, v[228:243]
	v_mfma_f32_32x32x2_f32 v[70:85], v69, v227, v[70:85]
	s_nop 15
	s_nop 15
	s_add_i32 s8, 0, 0x18000
	s_mul_i32 s5, s3, 0x1800
	s_add_i32 s5, s5, s8
	v_add_u32_e32 v2, s5, v50
	s_mul_i32 s5, s10, 0x1800
	s_add_i32 s5, s5, s4
	s_mul_i32 s4, s10, 0x90000
	ds_write_b32 v249, v228 offset:0
	ds_write_b32 v249, v70 offset:4
	ds_write_b32 v249, v229 offset:256
	ds_write_b32 v249, v71 offset:260
	ds_write_b32 v249, v230 offset:512
	ds_write_b32 v249, v72 offset:516
	ds_write_b32 v249, v231 offset:768
	ds_write_b32 v249, v73 offset:772
	ds_write_b32 v249, v232 offset:2048
	ds_write_b32 v249, v74 offset:2052
	ds_write_b32 v249, v233 offset:2304
	ds_write_b32 v249, v75 offset:2308
	ds_write_b32 v249, v234 offset:2560
	ds_write_b32 v249, v76 offset:2564
	ds_write_b32 v249, v235 offset:2816
	ds_write_b32 v249, v77 offset:2820
	ds_write_b32 v249, v236 offset:4096
	ds_write_b32 v249, v78 offset:4100
	ds_write_b32 v249, v237 offset:4352
	ds_write_b32 v249, v79 offset:4356
	ds_write_b32 v249, v238 offset:4608
	ds_write_b32 v249, v80 offset:4612
	ds_write_b32 v249, v239 offset:4864
	ds_write_b32 v249, v81 offset:4868
	v_or_b32_e32 v2, s5, v49
	s_mul_hi_i32 s5, s10, 0x90000
	s_add_u32 s4, s6, s4
	v_mov_b32_e32 v0, s30
	v_mov_b32_e32 v1, s31
	v_ashrrev_i32_e32 v3, 31, v2
	s_addc_u32 s5, s7, s5
	v_lshl_add_u64 v[0:1], v[2:3], 2, v[0:1]
	v_lshrrev_b32_e32 v4, 6, v48
	s_movk_i32 s6, 0x6000
	v_mov_b64_e32 v[2:3], s[4:5]
	v_mad_u64_u32 v[2:3], s[4:5], v4, s6, v[2:3]
	v_lshl_add_u64 v[2:3], v[2:3], 0, v[50:51]
	v_lshl_add_u64 v[2:3], s[26:27], 0, v[2:3]
	s_mov_b64 s[4:5], 0x100000
	v_lshl_add_u64 v[2:3], v[2:3], 0, s[4:5]
	v_lshlrev_b32_e32 v4, 2, v48
	s_movk_i32 s4, 0xff00
	v_and_or_b32 v4, v4, s4, v50
	v_add_u32_e32 v4, s8, v4
	v_add_u32_e32 v5, 0xfffffe00, v48
	s_mov_b64 s[4:5], 0
	s_mov_b64 s[6:7], 0x30000
	s_movk_i32 s8, 0x3ff
	s_waitcnt lgkmcnt(0)
	s_barrier
